# in_proj K loop: the back-to-back s_setprio 0 / s_setprio 1 in the middle of each MFMA cluster removed (priority stays raised through the cluster); on top of v112
# baseline (speedup 1.0000x reference)
; #define PG8_STAGE(bufoff, gbase, voff) do { _Pragma("unroll") for (int _i = 0; _i < 2; ++_i) \
;         __builtin_amdgcn_global_load_lds((const unsigned*)((const char*)(gbase) + (voff)[_i]), (LAS unsigned*)(lds + (bufoff) + ldsw + _i * 8192), 16, 0, 0); } while (0)
; #define PG8_LDA(dst, b, h) do { _Pragma("unroll") for (int m = 0; m < 4; ++m) _Pragma("unroll") for (int k = 0; k < 2; ++k) dst[m][k] = *(const LAS bf16x8*)(lds + PG8_SA(b, h) + aoff + m * 2048 + k * 1024); } while (0)
; #define PG8_LDB(dst, b, h) do { _Pragma("unroll") for (int n = 0; n < 2; ++n) _Pragma("unroll") for (int k = 0; k < 2; ++k) dst[n][k] = *(const LAS bf16x8*)(lds + PG8_SB(b, h) + boff + n * 2048 + k * 1024); } while (0)
; #define PG8_MMA(ai, bj, At, Bt) do { __builtin_amdgcn_s_setprio(1); _Pragma("unroll") for (int m = 0; m < 4; ++m) _Pragma("unroll") for (int n = 0; n < 2; ++n) _Pragma("unroll") for (int k = 0; k < 2; ++k) \
;         acc[ai][bj][m][n] = __builtin_amdgcn_mfma_f32_16x16x32_bf16(Bt[n][k], At[m][k], acc[ai][bj][m][n], 0, 0, 0); __builtin_amdgcn_s_setprio(0); } while (0)
; #define PG8_WAIT_V(n) asm volatile("s_waitcnt vmcnt(" #n ")" ::: "memory")
; #define PG8_WAIT_L(n) asm volatile("s_waitcnt lgkmcnt(" #n ")" ::: "memory")
; #define PG8_BAR __builtin_amdgcn_s_barrier()
; #define PG8_SCHED __builtin_amdgcn_sched_barrier(0)
; template <bool SP2 = true, class Epi, class Sched>
; __device__ __forceinline__ void gemm_phase(LAS unsigned char* lds, const int K, const int lda, const int ldb, const Sched& S, const Epi& E) {
;     ...
;             PG8_LDB(B0, 0, 0); PG8_LDB(B1, 0, 1); PG8_SCHED; PG8_LDA(At, 0, 0); PG8_STAGE(PG8_SA(1, 1), a1 + hstepA, voffA);
;             PG8_WAIT_V(8); PG8_WAIT_L(0); PG8_BAR; PG8_MMA(0, 0, At, B0); PG8_MMA(0, 1, At, B1); PG8_BAR; PG8_SCHED;
;             PG8_LDA(At, 0, 1); PG8_STAGE(PG8_SB(0, 0), b2, voffB); PG8_STAGE(PG8_SB(0, 1), b2 + hstepB, voffB); PG8_STAGE(PG8_SA(0, 0), a2, voffA);
;             PG8_WAIT_V(8); PG8_WAIT_L(0); PG8_BAR; PG8_MMA(1, 0, At, B0); PG8_MMA(1, 1, At, B1); PG8_BAR; PG8_SCHED;
.LBB0_254:
	s_add_u32 s10, s8, 0xfff80080
	s_addc_u32 s11, s9, -1
	s_add_i32 s48, 0, 0x10000
	s_cmp_eq_u32 s38, 28
	s_cselect_b32 s83, s29, s11
	s_cselect_b32 s82, s28, s10
	v_add_u32_e32 v160, s48, v164
	s_cselect_b32 s11, s31, s27
	s_cselect_b32 s10, s30, s25
	s_add_i32 s93, 0, 0x14000
	ds_read_b128 v[128:131], v160
	ds_read_b128 v[152:155], v160 offset:1024
	ds_read_b128 v[156:159], v160 offset:2048
	ds_read_b128 v[168:171], v160 offset:3072
	v_add_u32_e32 v160, s93, v164
	ds_read_b128 v[172:175], v160
	ds_read_b128 v[176:179], v160 offset:1024
	ds_read_b128 v[180:183], v160 offset:2048
	ds_read_b128 v[184:187], v160 offset:3072
	v_lshl_add_u64 v[160:161], s[8:9], 0, v[148:149]
	s_add_i32 m0, s81, 0xc000
	ds_read_b128 v[188:191], v166
	ds_read_b128 v[192:195], v166 offset:1024
	ds_read_b128 v[196:199], v166 offset:2048
	ds_read_b128 v[200:203], v166 offset:3072
	ds_read_b128 v[204:207], v166 offset:4096
	ds_read_b128 v[208:211], v166 offset:5120
	ds_read_b128 v[212:215], v166 offset:6144
	ds_read_b128 v[216:219], v166 offset:7168
	global_load_lds_dwordx4 v[160:161], off
	v_lshl_add_u64 v[160:161], s[8:9], 0, v[150:151]
	s_add_i32 m0, s81, 0xe000
	s_nop 0
	global_load_lds_dwordx4 v[160:161], off
	s_waitcnt vmcnt(8)
	s_waitcnt lgkmcnt(0)
	s_barrier
	s_setprio 1
	s_waitcnt lgkmcnt(0)
	v_mfma_f32_16x16x32_bf16 v[124:127], v[128:131], v[188:191], v[124:127]
	v_mfma_f32_16x16x32_bf16 v[120:123], v[156:159], v[188:191], v[120:123]
	v_mfma_f32_16x16x32_bf16 v[108:111], v[128:131], v[196:199], v[108:111]
	v_mfma_f32_16x16x32_bf16 v[104:107], v[156:159], v[196:199], v[104:107]
	v_mfma_f32_16x16x32_bf16 v[92:95], v[128:131], v[204:207], v[92:95]
	v_mfma_f32_16x16x32_bf16 v[88:91], v[156:159], v[204:207], v[88:91]
	v_mfma_f32_16x16x32_bf16 v[76:79], v[128:131], v[212:215], v[76:79]
	v_mfma_f32_16x16x32_bf16 v[72:75], v[156:159], v[212:215], v[72:75]
	v_mfma_f32_16x16x32_bf16 v[124:127], v[152:155], v[192:195], v[124:127]
	v_mfma_f32_16x16x32_bf16 v[120:123], v[168:171], v[192:195], v[120:123]
	v_mfma_f32_16x16x32_bf16 v[108:111], v[152:155], v[200:203], v[108:111]
	v_mfma_f32_16x16x32_bf16 v[104:107], v[168:171], v[200:203], v[104:107]
	v_mfma_f32_16x16x32_bf16 v[92:95], v[152:155], v[208:211], v[92:95]
	v_mfma_f32_16x16x32_bf16 v[88:91], v[168:171], v[208:211], v[88:91]
	v_mfma_f32_16x16x32_bf16 v[76:79], v[152:155], v[216:219], v[76:79]
	v_mfma_f32_16x16x32_bf16 v[72:75], v[168:171], v[216:219], v[72:75]
	v_mfma_f32_16x16x32_bf16 v[116:119], v[172:175], v[188:191], v[116:119]
	v_mfma_f32_16x16x32_bf16 v[112:115], v[180:183], v[188:191], v[112:115]
	v_mfma_f32_16x16x32_bf16 v[100:103], v[172:175], v[196:199], v[100:103]
	v_mfma_f32_16x16x32_bf16 v[96:99], v[180:183], v[196:199], v[96:99]
	v_mfma_f32_16x16x32_bf16 v[84:87], v[172:175], v[204:207], v[84:87]
	v_mfma_f32_16x16x32_bf16 v[80:83], v[180:183], v[204:207], v[80:83]
	v_mfma_f32_16x16x32_bf16 v[68:71], v[172:175], v[212:215], v[68:71]
	v_mfma_f32_16x16x32_bf16 v[64:67], v[180:183], v[212:215], v[64:67]
	v_mfma_f32_16x16x32_bf16 v[116:119], v[176:179], v[192:195], v[116:119]
	v_mfma_f32_16x16x32_bf16 v[112:115], v[184:187], v[192:195], v[112:115]
	v_mfma_f32_16x16x32_bf16 v[100:103], v[176:179], v[200:203], v[100:103]
	v_mfma_f32_16x16x32_bf16 v[96:99], v[184:187], v[200:203], v[96:99]
	v_mfma_f32_16x16x32_bf16 v[84:87], v[176:179], v[208:211], v[84:87]
	v_mfma_f32_16x16x32_bf16 v[80:83], v[184:187], v[208:211], v[80:83]
	v_mfma_f32_16x16x32_bf16 v[68:71], v[176:179], v[216:219], v[68:71]
	v_mfma_f32_16x16x32_bf16 v[64:67], v[184:187], v[216:219], v[64:67]
	s_setprio 0
	s_barrier
	s_add_i32 s48, s48, s70
	v_lshl_add_u64 v[160:161], s[10:11], 0, v[134:135]
	s_mov_b32 m0, s48
	ds_read_b128 v[188:191], v166 offset:16384
	ds_read_b128 v[192:195], v166 offset:17408
	ds_read_b128 v[196:199], v166 offset:18432
	ds_read_b128 v[200:203], v166 offset:19456
	ds_read_b128 v[204:207], v166 offset:20480
	ds_read_b128 v[208:211], v166 offset:21504
	ds_read_b128 v[212:215], v166 offset:22528
	ds_read_b128 v[216:219], v166 offset:23552
	global_load_lds_dwordx4 v[160:161], off
	s_add_i32 m0, s48, 0x2000
	s_add_u32 s48, s10, 0x80000
	v_lshl_add_u64 v[220:221], s[10:11], 0, v[138:139]
	s_addc_u32 s49, s11, 0
	s_add_i32 s93, s93, s70
	global_load_lds_dwordx4 v[220:221], off
	v_lshl_add_u64 v[222:223], s[48:49], 0, v[134:135]
	s_mov_b32 m0, s93
	v_lshl_add_u64 v[226:227], s[82:83], 0, v[136:137]
	global_load_lds_dwordx4 v[222:223], off
	v_lshl_add_u64 v[222:223], s[48:49], 0, v[138:139]
	s_add_i32 m0, s93, 0x2000
	s_nop 0
	global_load_lds_dwordx4 v[222:223], off
	v_lshl_add_u64 v[222:223], s[82:83], 0, v[132:133]
	s_mov_b32 m0, s81
	s_nop 0
	global_load_lds_dwordx4 v[222:223], off
	s_mov_b32 m0, s84
	s_nop 0
	global_load_lds_dwordx4 v[226:227], off
	s_waitcnt vmcnt(8)
	s_waitcnt lgkmcnt(0)
	s_barrier
; #define PG8_STAGE(bufoff, gbase, voff) do { _Pragma("unroll") for (int _i = 0; _i < 2; ++_i) \
;         __builtin_amdgcn_global_load_lds((const unsigned*)((const char*)(gbase) + (voff)[_i]), (LAS unsigned*)(lds + (bufoff) + ldsw + _i * 8192), 16, 0, 0); } while (0)
; #define PG8_LDA(dst, b, h) do { _Pragma("unroll") for (int m = 0; m < 4; ++m) _Pragma("unroll") for (int k = 0; k < 2; ++k) dst[m][k] = *(const LAS bf16x8*)(lds + PG8_SA(b, h) + aoff + m * 2048 + k * 1024); } while (0)
; #define PG8_LDB(dst, b, h) do { _Pragma("unroll") for (int n = 0; n < 2; ++n) _Pragma("unroll") for (int k = 0; k < 2; ++k) dst[n][k] = *(const LAS bf16x8*)(lds + PG8_SB(b, h) + boff + n * 2048 + k * 1024); } while (0)
; #define PG8_MMA(ai, bj, At, Bt) do { __builtin_amdgcn_s_setprio(1); _Pragma("unroll") for (int m = 0; m < 4; ++m) _Pragma("unroll") for (int n = 0; n < 2; ++n) _Pragma("unroll") for (int k = 0; k < 2; ++k) \
;         acc[ai][bj][m][n] = __builtin_amdgcn_mfma_f32_16x16x32_bf16(Bt[n][k], At[m][k], acc[ai][bj][m][n], 0, 0, 0); __builtin_amdgcn_s_setprio(0); } while (0)
; #define PG8_WAIT_V(n) asm volatile("s_waitcnt vmcnt(" #n ")" ::: "memory")
; #define PG8_WAIT_L(n) asm volatile("s_waitcnt lgkmcnt(" #n ")" ::: "memory")
; #define PG8_BAR __builtin_amdgcn_s_barrier()
; #define PG8_SCHED __builtin_amdgcn_sched_barrier(0)
; template <bool SP2 = true, class Epi, class Sched>
; __device__ __forceinline__ void gemm_phase(LAS unsigned char* lds, const int K, const int lda, const int ldb, const Sched& S, const Epi& E) {
;     ...
;             PG8_WAIT_V(8); PG8_WAIT_L(0); PG8_BAR; PG8_MMA(1, 0, At, B0); PG8_MMA(1, 1, At, B1); PG8_BAR; PG8_SCHED;
;             PG8_LDB(B0, 1, 0); PG8_LDB(B1, 1, 1); PG8_SCHED; PG8_LDA(At, 1, 0); PG8_STAGE(PG8_SA(0, 1), a2 + hstepA, voffA);
;             PG8_WAIT_V(8); PG8_WAIT_L(0); PG8_BAR; PG8_MMA(0, 0, At, B0); PG8_MMA(0, 1, At, B1); PG8_BAR; PG8_SCHED;
	s_setprio 1
	s_waitcnt lgkmcnt(0)
	v_mfma_f32_16x16x32_bf16 v[60:63], v[128:131], v[188:191], v[60:63]
	v_mfma_f32_16x16x32_bf16 v[56:59], v[156:159], v[188:191], v[56:59]
	v_mfma_f32_16x16x32_bf16 v[44:47], v[128:131], v[196:199], v[44:47]
	v_mfma_f32_16x16x32_bf16 v[40:43], v[156:159], v[196:199], v[40:43]
	v_mfma_f32_16x16x32_bf16 v[28:31], v[128:131], v[204:207], v[28:31]
	v_mfma_f32_16x16x32_bf16 v[24:27], v[156:159], v[204:207], v[24:27]
	v_mfma_f32_16x16x32_bf16 v[12:15], v[128:131], v[212:215], v[12:15]
	v_mfma_f32_16x16x32_bf16 v[8:11], v[156:159], v[212:215], v[8:11]
	v_mfma_f32_16x16x32_bf16 v[60:63], v[152:155], v[192:195], v[60:63]
	v_mfma_f32_16x16x32_bf16 v[56:59], v[168:171], v[192:195], v[56:59]
	v_mfma_f32_16x16x32_bf16 v[44:47], v[152:155], v[200:203], v[44:47]
	v_mfma_f32_16x16x32_bf16 v[40:43], v[168:171], v[200:203], v[40:43]
	v_mfma_f32_16x16x32_bf16 v[28:31], v[152:155], v[208:211], v[28:31]
	v_mfma_f32_16x16x32_bf16 v[24:27], v[168:171], v[208:211], v[24:27]
	v_mfma_f32_16x16x32_bf16 v[12:15], v[152:155], v[216:219], v[12:15]
	v_mfma_f32_16x16x32_bf16 v[8:11], v[168:171], v[216:219], v[8:11]
	v_mfma_f32_16x16x32_bf16 v[52:55], v[172:175], v[188:191], v[52:55]
	v_mfma_f32_16x16x32_bf16 v[48:51], v[180:183], v[188:191], v[48:51]
	v_mfma_f32_16x16x32_bf16 v[36:39], v[172:175], v[196:199], v[36:39]
	v_mfma_f32_16x16x32_bf16 v[32:35], v[180:183], v[196:199], v[32:35]
	v_mfma_f32_16x16x32_bf16 v[20:23], v[172:175], v[204:207], v[20:23]
	v_mfma_f32_16x16x32_bf16 v[16:19], v[180:183], v[204:207], v[16:19]
	v_mfma_f32_16x16x32_bf16 v[4:7], v[172:175], v[212:215], v[4:7]
	v_mfma_f32_16x16x32_bf16 v[0:3], v[180:183], v[212:215], v[0:3]
	v_mfma_f32_16x16x32_bf16 v[52:55], v[176:179], v[192:195], v[52:55]
	v_mfma_f32_16x16x32_bf16 v[48:51], v[184:187], v[192:195], v[48:51]
	v_mfma_f32_16x16x32_bf16 v[36:39], v[176:179], v[200:203], v[36:39]
	v_mfma_f32_16x16x32_bf16 v[32:35], v[184:187], v[200:203], v[32:35]
	v_mfma_f32_16x16x32_bf16 v[20:23], v[176:179], v[208:211], v[20:23]
	v_mfma_f32_16x16x32_bf16 v[16:19], v[184:187], v[208:211], v[16:19]
	v_mfma_f32_16x16x32_bf16 v[4:7], v[176:179], v[216:219], v[4:7]
	v_mfma_f32_16x16x32_bf16 v[0:3], v[184:187], v[216:219], v[0:3]
	s_setprio 0
	s_barrier
	s_add_i32 s93, 0, 0x18000
	v_add_u32_e32 v167, s93, v164
	s_add_i32 s94, 0, 0x1c000
	ds_read_b128 v[128:131], v167
	ds_read_b128 v[152:155], v167 offset:1024
	ds_read_b128 v[156:159], v167 offset:2048
	ds_read_b128 v[168:171], v167 offset:3072
	v_add_u32_e32 v167, s94, v164
	ds_read_b128 v[172:175], v167
	ds_read_b128 v[176:179], v167 offset:1024
	ds_read_b128 v[180:183], v167 offset:2048
	ds_read_b128 v[184:187], v167 offset:3072
	s_add_u32 s48, s82, 0x80000
	s_addc_u32 s49, s83, 0
	s_mov_b32 m0, s85
	v_lshl_add_u64 v[228:229], s[48:49], 0, v[132:133]
	ds_read_b128 v[188:191], v166 offset:32768
	ds_read_b128 v[192:195], v166 offset:33792
	ds_read_b128 v[196:199], v166 offset:34816
	ds_read_b128 v[200:203], v166 offset:35840
	ds_read_b128 v[204:207], v166 offset:36864
	ds_read_b128 v[208:211], v166 offset:37888
	ds_read_b128 v[212:215], v166 offset:38912
	ds_read_b128 v[216:219], v166 offset:39936
	global_load_lds_dwordx4 v[228:229], off
	v_lshl_add_u64 v[228:229], s[48:49], 0, v[136:137]
	s_mov_b32 m0, s86
	s_nop 0
	global_load_lds_dwordx4 v[228:229], off
	s_waitcnt vmcnt(8)
	s_waitcnt lgkmcnt(0)
	s_barrier
	s_setprio 1
	s_waitcnt lgkmcnt(0)
	v_mfma_f32_16x16x32_bf16 v[124:127], v[128:131], v[188:191], v[124:127]
	v_mfma_f32_16x16x32_bf16 v[120:123], v[156:159], v[188:191], v[120:123]
	v_mfma_f32_16x16x32_bf16 v[108:111], v[128:131], v[196:199], v[108:111]
	v_mfma_f32_16x16x32_bf16 v[104:107], v[156:159], v[196:199], v[104:107]
	v_mfma_f32_16x16x32_bf16 v[92:95], v[128:131], v[204:207], v[92:95]
	v_mfma_f32_16x16x32_bf16 v[88:91], v[156:159], v[204:207], v[88:91]
	v_mfma_f32_16x16x32_bf16 v[76:79], v[128:131], v[212:215], v[76:79]
	v_mfma_f32_16x16x32_bf16 v[72:75], v[156:159], v[212:215], v[72:75]
	v_mfma_f32_16x16x32_bf16 v[124:127], v[152:155], v[192:195], v[124:127]
	v_mfma_f32_16x16x32_bf16 v[120:123], v[168:171], v[192:195], v[120:123]
	v_mfma_f32_16x16x32_bf16 v[108:111], v[152:155], v[200:203], v[108:111]
	v_mfma_f32_16x16x32_bf16 v[104:107], v[168:171], v[200:203], v[104:107]
	v_mfma_f32_16x16x32_bf16 v[92:95], v[152:155], v[208:211], v[92:95]
	v_mfma_f32_16x16x32_bf16 v[88:91], v[168:171], v[208:211], v[88:91]
	v_mfma_f32_16x16x32_bf16 v[76:79], v[152:155], v[216:219], v[76:79]
	v_mfma_f32_16x16x32_bf16 v[72:75], v[168:171], v[216:219], v[72:75]
	v_mfma_f32_16x16x32_bf16 v[116:119], v[172:175], v[188:191], v[116:119]
	v_mfma_f32_16x16x32_bf16 v[112:115], v[180:183], v[188:191], v[112:115]
	v_mfma_f32_16x16x32_bf16 v[100:103], v[172:175], v[196:199], v[100:103]
	v_mfma_f32_16x16x32_bf16 v[96:99], v[180:183], v[196:199], v[96:99]
	v_mfma_f32_16x16x32_bf16 v[84:87], v[172:175], v[204:207], v[84:87]
	v_mfma_f32_16x16x32_bf16 v[80:83], v[180:183], v[204:207], v[80:83]
	v_mfma_f32_16x16x32_bf16 v[68:71], v[172:175], v[212:215], v[68:71]
	v_mfma_f32_16x16x32_bf16 v[64:67], v[180:183], v[212:215], v[64:67]
	v_mfma_f32_16x16x32_bf16 v[116:119], v[176:179], v[192:195], v[116:119]
	v_mfma_f32_16x16x32_bf16 v[112:115], v[184:187], v[192:195], v[112:115]
	v_mfma_f32_16x16x32_bf16 v[100:103], v[176:179], v[200:203], v[100:103]
	v_mfma_f32_16x16x32_bf16 v[96:99], v[184:187], v[200:203], v[96:99]
	v_mfma_f32_16x16x32_bf16 v[84:87], v[176:179], v[208:211], v[84:87]
	v_mfma_f32_16x16x32_bf16 v[80:83], v[184:187], v[208:211], v[80:83]
	v_mfma_f32_16x16x32_bf16 v[68:71], v[176:179], v[216:219], v[68:71]
	v_mfma_f32_16x16x32_bf16 v[64:67], v[184:187], v[216:219], v[64:67]
	s_setprio 0
	s_barrier
; #define PG8_STAGE(bufoff, gbase, voff) do { _Pragma("unroll") for (int _i = 0; _i < 2; ++_i) \
;         __builtin_amdgcn_global_load_lds((const unsigned*)((const char*)(gbase) + (voff)[_i]), (LAS unsigned*)(lds + (bufoff) + ldsw + _i * 8192), 16, 0, 0); } while (0)
; #define PG8_LDA(dst, b, h) do { _Pragma("unroll") for (int m = 0; m < 4; ++m) _Pragma("unroll") for (int k = 0; k < 2; ++k) dst[m][k] = *(const LAS bf16x8*)(lds + PG8_SA(b, h) + aoff + m * 2048 + k * 1024); } while (0)
; #define PG8_WAIT_V(n) asm volatile("s_waitcnt vmcnt(" #n ")" ::: "memory")
; template <bool SP2 = true, class Epi, class Sched>
; __device__ __forceinline__ void gemm_phase(LAS unsigned char* lds, const int K, const int lda, const int ldb, const Sched& S, const Epi& E) {
;     ...
;             PG8_LDA(At, 1, 1); PG8_STAGE(PG8_SB(1, 0), b3, voffB); PG8_STAGE(PG8_SB(1, 1), b3 + hstepB, voffB); PG8_STAGE(PG8_SA(1, 0), a3, voffA);
;             PG8_WAIT_V(8); PG8_WAIT_L(0); PG8_BAR; PG8_MMA(1, 0, At, B0); PG8_MMA(1, 1, At, B1); PG8_BAR; PG8_SCHED;
;             } else {
;             PG8_LDB(B0, 0, 0); PG8_SCHED; PG8_LDA(At, 0, 0); PG8_STAGE(PG8_SA(1, 1), a1 + hstepA, voffA);
;             PG8_WAIT_L(8); PG8_BAR; PG8_WAIT_L(0); PG8_MMA(0, 0, At, B0); PG8_BAR; PG8_SCHED;
;             PG8_LDB(B1, 0, 1); PG8_STAGE(PG8_SB(0, 0), b2, voffB);
;             PG8_BAR; PG8_WAIT_L(0); PG8_MMA(0, 1, At, B1); PG8_BAR;
;             PG8_LDA(At, 0, 1); PG8_STAGE(PG8_SA(0, 0), a2, voffA);
;             PG8_BAR; PG8_WAIT_L(0); PG8_MMA(1, 0, At, B0); PG8_BAR; PG8_SCHED;
;             PG8_STAGE(PG8_SB(0, 1), b2 + hstepB, voffB);
;             PG8_WAIT_V(6); PG8_BAR; PG8_MMA(1, 1, At, B1); PG8_BAR;
;             PG8_LDB(B0, 1, 0); PG8_SCHED; PG8_LDA(At, 1, 0); PG8_STAGE(PG8_SA(0, 1), a2 + hstepA, voffA);
;             PG8_WAIT_L(8); PG8_BAR; PG8_WAIT_L(0); PG8_MMA(0, 0, At, B0); PG8_BAR; PG8_SCHED;
;             PG8_LDB(B1, 1, 1); PG8_STAGE(PG8_SB(1, 0), b3, voffB);
;             PG8_BAR; PG8_WAIT_L(0); PG8_MMA(0, 1, At, B1); PG8_BAR;
;             PG8_LDA(At, 1, 1); PG8_STAGE(PG8_SA(1, 0), a3, voffA);
;             PG8_BAR; PG8_WAIT_L(0); PG8_MMA(1, 0, At, B0); PG8_BAR; PG8_SCHED;
;             PG8_STAGE(PG8_SB(1, 1), b3 + hstepB, voffB);
;             PG8_WAIT_V(6); PG8_BAR; PG8_MMA(1, 1, At, B1); PG8_BAR;
;             }
;         }
;         if (wr == 0) PG8_BAR;
	s_add_i32 s48, s93, s70
	v_lshl_add_u64 v[160:161], v[160:161], 0, s[72:73]
	s_mov_b32 m0, s48
	ds_read_b128 v[188:191], v166 offset:49152
	ds_read_b128 v[192:195], v166 offset:50176
	ds_read_b128 v[196:199], v166 offset:51200
	ds_read_b128 v[200:203], v166 offset:52224
	ds_read_b128 v[204:207], v166 offset:53248
	ds_read_b128 v[208:211], v166 offset:54272
	ds_read_b128 v[212:215], v166 offset:55296
	ds_read_b128 v[216:219], v166 offset:56320
	global_load_lds_dwordx4 v[160:161], off
	s_add_i32 m0, s48, 0x2000
	s_add_u32 s10, s10, 0x80080
	v_lshl_add_u64 v[160:161], v[220:221], 0, s[72:73]
	s_addc_u32 s11, s11, 0
	s_add_i32 s48, s94, s70
	global_load_lds_dwordx4 v[160:161], off
	v_lshl_add_u64 v[160:161], s[10:11], 0, v[134:135]
	s_mov_b32 m0, s48
	s_nop 0
	global_load_lds_dwordx4 v[160:161], off
	v_lshl_add_u64 v[160:161], s[10:11], 0, v[138:139]
	s_add_i32 m0, s48, 0x2000
	s_nop 0
	global_load_lds_dwordx4 v[160:161], off
	v_lshl_add_u64 v[160:161], v[222:223], 0, s[72:73]
	s_mov_b32 m0, s88
	s_nop 0
	global_load_lds_dwordx4 v[160:161], off
	v_lshl_add_u64 v[160:161], v[226:227], 0, s[72:73]
	s_mov_b32 m0, s89
	s_nop 0
	global_load_lds_dwordx4 v[160:161], off
	s_waitcnt vmcnt(8)
	s_waitcnt lgkmcnt(0)
	s_barrier
	s_setprio 1
	s_waitcnt lgkmcnt(0)
	v_mfma_f32_16x16x32_bf16 v[60:63], v[128:131], v[188:191], v[60:63]
	v_mfma_f32_16x16x32_bf16 v[56:59], v[156:159], v[188:191], v[56:59]
	v_mfma_f32_16x16x32_bf16 v[44:47], v[128:131], v[196:199], v[44:47]
	v_mfma_f32_16x16x32_bf16 v[40:43], v[156:159], v[196:199], v[40:43]
	v_mfma_f32_16x16x32_bf16 v[28:31], v[128:131], v[204:207], v[28:31]
	v_mfma_f32_16x16x32_bf16 v[24:27], v[156:159], v[204:207], v[24:27]
	v_mfma_f32_16x16x32_bf16 v[12:15], v[128:131], v[212:215], v[12:15]
	v_mfma_f32_16x16x32_bf16 v[8:11], v[156:159], v[212:215], v[8:11]
	v_mfma_f32_16x16x32_bf16 v[60:63], v[152:155], v[192:195], v[60:63]
	v_mfma_f32_16x16x32_bf16 v[56:59], v[168:171], v[192:195], v[56:59]
	v_mfma_f32_16x16x32_bf16 v[44:47], v[152:155], v[200:203], v[44:47]
	v_mfma_f32_16x16x32_bf16 v[40:43], v[168:171], v[200:203], v[40:43]
	v_mfma_f32_16x16x32_bf16 v[28:31], v[152:155], v[208:211], v[28:31]
	v_mfma_f32_16x16x32_bf16 v[24:27], v[168:171], v[208:211], v[24:27]
	v_mfma_f32_16x16x32_bf16 v[12:15], v[152:155], v[216:219], v[12:15]
	v_mfma_f32_16x16x32_bf16 v[8:11], v[168:171], v[216:219], v[8:11]
	v_mfma_f32_16x16x32_bf16 v[52:55], v[172:175], v[188:191], v[52:55]
	v_mfma_f32_16x16x32_bf16 v[48:51], v[180:183], v[188:191], v[48:51]
	v_mfma_f32_16x16x32_bf16 v[36:39], v[172:175], v[196:199], v[36:39]
	v_mfma_f32_16x16x32_bf16 v[32:35], v[180:183], v[196:199], v[32:35]
	v_mfma_f32_16x16x32_bf16 v[20:23], v[172:175], v[204:207], v[20:23]
	v_mfma_f32_16x16x32_bf16 v[16:19], v[180:183], v[204:207], v[16:19]
	v_mfma_f32_16x16x32_bf16 v[4:7], v[172:175], v[212:215], v[4:7]
	v_mfma_f32_16x16x32_bf16 v[0:3], v[180:183], v[212:215], v[0:3]
	v_mfma_f32_16x16x32_bf16 v[52:55], v[176:179], v[192:195], v[52:55]
	v_mfma_f32_16x16x32_bf16 v[48:51], v[184:187], v[192:195], v[48:51]
	v_mfma_f32_16x16x32_bf16 v[36:39], v[176:179], v[200:203], v[36:39]
	v_mfma_f32_16x16x32_bf16 v[32:35], v[184:187], v[200:203], v[32:35]
	v_mfma_f32_16x16x32_bf16 v[20:23], v[176:179], v[208:211], v[20:23]
	v_mfma_f32_16x16x32_bf16 v[16:19], v[184:187], v[208:211], v[16:19]
	v_mfma_f32_16x16x32_bf16 v[4:7], v[176:179], v[216:219], v[4:7]
	v_mfma_f32_16x16x32_bf16 v[0:3], v[184:187], v[216:219], v[0:3]
	s_setprio 0
	s_barrier
	s_add_i32 s38, s38, 2
	s_add_u32 s8, s8, 0x100
	s_addc_u32 s9, s9, 0
	s_add_u32 s25, s25, 0x100
	s_addc_u32 s27, s27, 0
	s_cmp_gt_u32 s38, 29
	s_cbranch_scc0 .LBB0_254
	s_and_b64 vcc, exec, s[22:23]
	s_cbranch_vccz .LBB0_257
	s_barrier
